# P2 state scan: LDS-DMA ring run three steps ahead with counted waits, on top of the non-temporal read-once streams
# speedup vs baseline: 1.0150x; 1.0150x over previous
; __device__ __forceinline__ int crow(int r, int hi) { return (r & 3) + 8 * (r >> 2) + 4 * hi; }
; __device__ __forceinline__ void ret_state_scan(const bf16_t* __restrict__ proj, bf16_t* __restrict__ state, int b, int h, int d4, int e2, char* lds) {
;     int tid_ = threadIdx.x; asm volatile("" : "+v"(tid_));
;     const int tid = tid_, wid = __builtin_amdgcn_readfirstlane(tid >> 6), lane = tid & 63, r32 = lane & 31, hi = lane >> 5;
;     const int wd = wid & 1, we = wid >> 1;
;     constexpr int STG = 24576;
;     const bf16_t* Kp = proj + (size_t)(b * SEQ) * LDQ + 4096 + h * 256 + d4 * 64;
;     const bf16_t* Vp = proj + (size_t)(b * SEQ) * LDQ + 5120 + h * 256 + e2 * 128;
;     bf16_t* Sp = state + ((size_t)((b * 4 + h) * 16) * 256 + d4 * 64 + wd * 32) * 256 + e2 * 128 + we * 32;
;     const int lb = wid * 1024 + lane * 16, stv = lb >> 9, rowin = (lb >> 6) & 7, ch = (lb >> 4) & 3;
;     const int kkk = ((stv >> 1) << 3) | rowin, keyk = (kkk & ~0xC) | ((kkk & 4) << 1) | ((kkk & 8) >> 1);
;     const bf16_t* kg = Kp + (size_t)keyk * LDQ + (stv & 1) * 32 + ch * 8;
;     const int kkv = ((stv >> 2) << 3) | rowin, keyv = (kkv & ~0xC) | ((kkv & 4) << 1) | ((kkv & 8) >> 1);
;     const bf16_t* vg = Vp + (size_t)keyv * LDQ + (stv & 3) * 32 + ch * 8;
;     ...
;     f32x16 R;
; #pragma unroll
;     for (int r = 0; r < 16; ++r) R[r] = 0.f;
;     const int rb = (int)(uintptr_t)lds + v_rd_base(lane);
;     FA_DMA(0, 0); FA_DMA(1, 1);
;     for (int st = 0; st < 32; ++st) {
;         if ((st & 1) == 0 && st > 0) {
;             bf16_t* dst = Sp + (size_t)(st >> 1) * 65536;
; #pragma unroll
;             for (int r = 0; r < 16; ++r) { const float v = R[r]; const float vn = __shfl_xor(v, 1);
;                 if ((r32 & 1) == 0) *(unsigned*)(dst + (size_t)crow(r, hi) * 256 + r32) = cvtpk(v, vn); } }
;         if (st + 2 < 32) { FA_DMA(st + 2, (st + 2) & 3); asm volatile("s_waitcnt vmcnt(6)" ::: "memory"); }
;         else asm volatile("s_waitcnt vmcnt(0)" ::: "memory");
;         __builtin_amdgcn_s_barrier(); asm volatile("" ::: "memory");
;         const int ka = rb + (st & 3) * STG + wd * 512, va = rb + (st & 3) * STG + 8192 + we * 512;
;     ...
;         s16x4 al[4], ah[4], bl[4], bh[4];
;         FA_TR(al[0], ka, 0); FA_TR(ah[0], ka, 1024); FA_TR(al[1], ka, 2048); FA_TR(ah[1], ka, 3072); FA_TR(al[2], ka, 4096); FA_TR(ah[2], ka, 5120); FA_TR(al[3], ka, 6144); FA_TR(ah[3], ka, 7168);
.LBB0_211:
	s_nop 1
	v_mov_b32_e32 v8, v185
	s_lshl_b32 s1, s26, 1
	s_bfe_u32 s0, s33, 0x20003
	v_readfirstlane_b32 s34, v8
	s_and_b32 s42, s1, 0x180
	s_lshl_b32 s1, s28, 1
	s_ashr_i32 s24, s33, 5
	s_ashr_i32 s35, s34, 6
	s_lshl_b32 s41, s0, 9
	s_and_b32 s38, s1, 0x100
	s_lshl_b32 s40, s0, 4
	s_and_b32 s39, s26, 0xc0
	s_and_b32 s36, s35, 1
	s_ashr_i32 s37, s34, 7
	s_lshl_b32 s43, s24, 11
	s_mul_i32 s46, s24, 0x1c00000
	s_mul_hi_i32 s47, s43, 0x3800
	s_add_u32 s0, s84, s46
	s_addc_u32 s1, s85, s47
	s_lshl_b32 s48, s33, 6
	s_lshl_b32 s44, s33, 8
	s_and_b32 s25, s48, 0x600
	s_and_b32 s44, s44, 0x100
	s_add_u32 s49, s0, s25
	s_addc_u32 s50, s1, 0
	s_add_u32 s0, s49, s44
	s_addc_u32 s1, s50, 0
	s_add_u32 s0, s0, 0x2800
	s_addc_u32 s1, s1, 0
	s_lshl_b32 s51, s35, 10
	s_lshl_b32 s52, s35, 3
	s_lshl_b32 s35, s35, 2
	v_lshlrev_b32_e32 v6, 4, v8
	s_and_b32 s52, s52, -16
	s_and_b32 s35, s35, 4
	s_ashr_i32 s34, s34, 4
	v_and_b32_e32 v0, 0x3f0, v6
	s_or_b32 s52, s52, s35
	s_and_b32 s35, s34, -16
	s_lshr_b32 s34, s34, 1
	v_or_b32_e32 v2, s51, v0
	v_lshrrev_b32_e32 v0, 1, v8
	s_and_b32 s34, s34, 4
	v_bfe_u32 v29, v8, 2, 2
	v_and_b32_e32 v54, 8, v0
	s_or_b32 s53, s35, s34
	v_or3_b32 v3, s53, v29, v54
	v_mov_b64_e32 v[0:1], s[0:1]
	s_lshl_b32 s45, s24, 6
	s_lshl_b32 s24, s37, 5
	v_mad_i64_i32 v[0:1], s[0:1], v3, s30, v[0:1]
	s_lshl_b32 s44, s36, 5
	s_ashr_i32 s25, s24, 31
	s_and_b32 s0, s48, 0x180
	s_add_u32 s0, s49, s0
	s_addc_u32 s1, s50, 0
	s_add_u32 s0, s0, 0x2000
	s_addc_u32 s1, s1, 0
	v_or3_b32 v4, s52, v29, v54
	v_lshrrev_b32_e32 v5, 3, v2
	v_mov_b64_e32 v[2:3], s[0:1]
	v_mad_i64_i32 v[2:3], s[0:1], v4, s30, v[2:3]
	v_and_b32_e32 v24, 64, v5
	v_mov_b32_e32 v25, v17
	v_and_b32_e32 v16, 0xc0, v5
	v_lshl_add_u64 v[2:3], v[2:3], 0, v[24:25]
	v_and_b32_e32 v50, 48, v6
	v_mov_b32_e32 v51, v17
	s_add_i32 s34, s51, 0
	v_lshl_add_u64 v[0:1], v[0:1], 0, v[16:17]
	v_lshl_add_u64 v[2:3], v[2:3], 0, v[50:51]
	s_mov_b32 m0, s34
	v_lshl_add_u64 v[0:1], v[0:1], 0, v[50:51]
	global_load_lds_dwordx4 v[2:3], off
	s_add_i32 m0, s34, 0x2000
	v_lshl_add_u64 v[4:5], v[0:1], 0, s[8:9]
	global_load_lds_dwordx4 v[0:1], off
	s_add_i32 m0, s34, 0x4000
	s_mov_b32 s35, 3
	global_load_lds_dwordx4 v[4:5], off
	v_lshl_add_u64 v[4:5], v[2:3], 0, s[10:11]
	s_add_i32 m0, s34, 0x6000
	v_lshl_add_u64 v[2:3], v[2:3], 0, s[14:15]
	global_load_lds_dwordx4 v[4:5], off
	v_lshl_add_u64 v[4:5], v[0:1], 0, s[10:11]
	s_add_i32 m0, s34, 0x8000
	v_and_b32_e32 v25, 31, v8
	global_load_lds_dwordx4 v[4:5], off
	s_add_i32 m0, s34, 0xa000
	v_lshl_add_u64 v[4:5], v[0:1], 0, s[12:13]
	s_cmp_lg_u32 0, -1
	global_load_lds_dwordx4 v[4:5], off
	s_cselect_b32 s48, 0, 0
	s_add_i32 m0, s34, 0xc000
	s_lshl_b32 s36, s36, 9
	global_load_lds_dwordx4 v[2:3], off
	v_lshl_add_u64 v[2:3], v[0:1], 0, s[14:15]
	s_add_i32 m0, s34, 0xe000
	v_lshl_add_u64 v[0:1], v[0:1], 0, s[16:17]
	global_load_lds_dwordx4 v[2:3], off
	s_add_i32 m0, s34, 0x10000
	v_lshlrev_b32_e32 v2, 1, v8
	global_load_lds_dwordx4 v[0:1], off
	v_lshlrev_b32_e32 v0, 3, v8
	v_and_b32_e32 v2, 32, v2
	v_and_b32_e32 v1, 0xc0, v6
	v_and_or_b32 v0, v0, s31, v2
	v_add3_u32 v28, v1, s48, v0
	s_waitcnt vmcnt(6)
	s_barrier
	v_and_b32_e32 v2, 1, v8
	v_add_u32_e32 v4, s36, v28
	ds_read_b64_tr_b16 v[0:1], v4 offset:0
	v_cmp_eq_u32_e64 s[0:1], 0, v2
	ds_read_b64_tr_b16 v[2:3], v4 offset:0x400
	ds_read_b64_tr_b16 v[20:21], v4 offset:0x800
	ds_read_b64_tr_b16 v[22:23], v4 offset:0xc00
	ds_read_b64_tr_b16 v[30:31], v4 offset:0x1000
	ds_read_b64_tr_b16 v[32:33], v4 offset:0x1400
	s_lshl_b32 s37, s37, 9
	ds_read_b64_tr_b16 v[34:35], v4 offset:0x1800
	s_addk_i32 s37, 0x2000
	ds_read_b64_tr_b16 v[36:37], v4 offset:0x1c00
	v_add_u32_e32 v9, s37, v28
	ds_read_b64_tr_b16 v[4:5], v9 offset:0
	ds_read_b64_tr_b16 v[6:7], v9 offset:0x800
	ds_read_b64_tr_b16 v[38:39], v9 offset:0x1000
	ds_read_b64_tr_b16 v[40:41], v9 offset:0x1800
	ds_read_b64_tr_b16 v[42:43], v9 offset:0x2000
	ds_read_b64_tr_b16 v[44:45], v9 offset:0x2800
	ds_read_b64_tr_b16 v[46:47], v9 offset:0x3000
	ds_read_b64_tr_b16 v[48:49], v9 offset:0x3800
	s_waitcnt lgkmcnt(0)
	v_lshlrev_b32_e32 v8, 6, v8
	v_and_b32_e32 v52, 0x800, v8
	v_mfma_f32_32x32x16_bf16 v[0:15], v[0:3], v[4:7], 0
	s_add_u32 s46, s46, 0xaaa2000
	s_addc_u32 s47, s47, 0
	v_or3_b32 v51, s52, v54, v29
	v_mov_b64_e32 v[18:19], s[46:47]
	v_mad_i64_i32 v[18:19], s[46:47], v51, s30, v[18:19]
	v_or_b32_e32 v18, s41, v18
	v_mfma_f32_32x32x16_bf16 v[0:15], v[20:23], v[38:41], v[0:15]
	v_or_b32_e32 v18, s42, v18
	v_or3_b32 v18, v18, v24, v50
	v_or3_b32 v24, s53, v54, v29
	v_mad_i64_i32 v[20:21], s[46:47], v24, s30, 0
	v_mad_i64_i32 v[20:21], s[42:43], s43, v26, v[20:21]
	v_mfma_f32_32x32x16_bf16 v[0:15], v[30:33], v[42:45], v[0:15]
	s_or_b32 s40, s45, s40
	v_or_b32_e32 v20, s41, v20
	s_ashr_i32 s41, s40, 31
	s_lshl_b64 s[40:41], s[40:41], 8
	s_or_b32 s39, s40, s39
	s_or_b32 s40, s39, s44
	s_lshl_b64 s[40:41], s[40:41], 9
	v_mfma_f32_32x32x16_bf16 v[0:15], v[34:37], v[46:49], v[0:15]
	s_lshl_b64 s[24:25], s[24:25], 1
	s_add_u32 s24, s24, s38
	s_addc_u32 s25, s25, 0
	s_add_u32 s24, s24, s40
	v_mov_b32_e32 v53, v17
	s_addc_u32 s25, s25, s41
	v_or_b32_e32 v20, s38, v20
	v_lshl_add_u64 v[22:23], s[24:25], 0, v[52:53]
	v_or3_b32 v20, v20, v16, v50
	v_lshl_or_b32 v22, v25, 1, v22
	s_add_i32 s25, s34, 0x12000
	v_lshl_add_u64 v[24:25], s[76:77], 0, v[18:19]
	s_mov_b32 m0, s25
	s_nop 0
	global_load_lds_dwordx4 v[24:25], off
	v_lshl_add_u64 v[24:25], s[76:77], 0, v[20:21]
	v_lshl_add_u64 v[30:31], v[24:25], 0, s[18:19]
	s_add_i32 m0, s25, 0x2000
	v_lshl_add_u64 v[24:25], v[24:25], 0, s[20:21]
	global_load_lds_dwordx4 v[30:31], off
	s_add_i32 m0, s25, 0x4000
	s_nop 0
	global_load_lds_dwordx4 v[24:25], off
	s_branch .LBB0_213
; #define SBAR() __builtin_amdgcn_sched_barrier(0)
; __device__ __forceinline__ int crow(int r, int hi) { return (r & 3) + 8 * (r >> 2) + 4 * hi; }
; __device__ __forceinline__ unsigned cvtpk(float lo, float hi) { unsigned r; asm volatile("v_cvt_pk_bf16_f32 %0, %1, %2" : "=v"(r) : "v"(lo), "v"(hi)); return r; }
; #define FA_TR(dst, base, off) asm volatile("ds_read_b64_tr_b16 %0, %1 offset:%2" : "=&v"(dst) : "v"(base), "i"(off) : "memory")
; __device__ __forceinline__ void ret_state_scan(const bf16_t* __restrict__ proj, bf16_t* __restrict__ state, int b, int h, int d4, int e2, char* lds) {
;     ...
;     for (int st = 0; st < 32; ++st) {
;         if ((st & 1) == 0 && st > 0) {
;             bf16_t* dst = Sp + (size_t)(st >> 1) * 65536;
; #pragma unroll
;             for (int r = 0; r < 16; ++r) { const float v = R[r]; const float vn = __shfl_xor(v, 1);
;                 if ((r32 & 1) == 0) *(unsigned*)(dst + (size_t)crow(r, hi) * 256 + r32) = cvtpk(v, vn); } }
;         if (st + 2 < 32) { FA_DMA(st + 2, (st + 2) & 3); asm volatile("s_waitcnt vmcnt(6)" ::: "memory"); }
;         else asm volatile("s_waitcnt vmcnt(0)" ::: "memory");
;         __builtin_amdgcn_s_barrier(); asm volatile("" ::: "memory");
;         const int ka = rb + (st & 3) * STG + wd * 512, va = rb + (st & 3) * STG + 8192 + we * 512;
;     ...
;         s16x4 al[4], ah[4], bl[4], bh[4];
;         FA_TR(al[0], ka, 0); FA_TR(ah[0], ka, 1024); FA_TR(al[1], ka, 2048); FA_TR(ah[1], ka, 3072); FA_TR(al[2], ka, 4096); FA_TR(ah[2], ka, 5120); FA_TR(al[3], ka, 6144); FA_TR(ah[3], ka, 7168);
;         FA_TR(bl[0], va, 0); FA_TR(bh[0], va, 2048); FA_TR(bl[1], va, 4096); FA_TR(bh[1], va, 6144); FA_TR(bl[2], va, 8192); FA_TR(bh[2], va, 10240); FA_TR(bl[3], va, 12288); FA_TR(bh[3], va, 14336);
;         asm volatile("s_waitcnt lgkmcnt(0)" ::: "memory"); SBAR();
; #pragma unroll
;         for (int ks = 0; ks < 4; ++ks)
;             R = __builtin_amdgcn_mfma_f32_32x32x16_bf16((bf16x8){al[ks][0], al[ks][1], al[ks][2], al[ks][3], ah[ks][0], ah[ks][1], ah[ks][2], ah[ks][3]},
;                                                         (bf16x8){bl[ks][0], bl[ks][1], bl[ks][2], bl[ks][3], bh[ks][0], bh[ks][1], bh[ks][2], bh[ks][3]}, R, 0, 0, 0);
.LBB0_212:
	s_and_b32 s24, s38, 3
	s_mulk_i32 s24, 0x6000
	s_barrier
	s_cmp_gt_u32 s35, 30
	s_cbranch_scc1 .Lp2_nodma
	s_add_i32 s25, s35, 1
	s_and_b32 s25, s25, 3
	s_mulk_i32 s25, 0x6000
	s_add_i32 s25, s34, s25
	v_lshl_add_u64 v[24:25], s[76:77], 0, v[18:19]
	v_lshl_add_u64 v[24:25], v[24:25], 0, s[10:11]
	s_mov_b32 m0, s25
	s_nop 0
	global_load_lds_dwordx4 v[24:25], off
	v_lshl_add_u64 v[24:25], s[76:77], 0, v[20:21]
	v_lshl_add_u64 v[24:25], v[24:25], 0, s[10:11]
	v_lshl_add_u64 v[30:31], v[24:25], 0, s[18:19]
	s_add_i32 m0, s25, 0x2000
	v_lshl_add_u64 v[24:25], v[24:25], 0, s[20:21]
	global_load_lds_dwordx4 v[30:31], off
	s_add_i32 m0, s25, 0x4000
	s_nop 0
	global_load_lds_dwordx4 v[24:25], off
.Lp2_nodma:
	s_waitcnt lgkmcnt(0)
	v_add_u32_e32 v16, s24, v28
	v_add_u32_e32 v24, s36, v16
	ds_read_b64_tr_b16 v[30:31], v24 offset:0
	ds_read_b64_tr_b16 v[32:33], v24 offset:0x400
	ds_read_b64_tr_b16 v[34:35], v24 offset:0x800
	ds_read_b64_tr_b16 v[36:37], v24 offset:0xc00
	ds_read_b64_tr_b16 v[38:39], v24 offset:0x1000
	ds_read_b64_tr_b16 v[40:41], v24 offset:0x1400
	ds_read_b64_tr_b16 v[42:43], v24 offset:0x1800
	ds_read_b64_tr_b16 v[44:45], v24 offset:0x1c00
	v_add_u32_e32 v16, s37, v16
	ds_read_b64_tr_b16 v[46:47], v16 offset:0
	ds_read_b64_tr_b16 v[48:49], v16 offset:0x800
	ds_read_b64_tr_b16 v[50:51], v16 offset:0x1000
	ds_read_b64_tr_b16 v[52:53], v16 offset:0x1800
	ds_read_b64_tr_b16 v[54:55], v16 offset:0x2000
	ds_read_b64_tr_b16 v[56:57], v16 offset:0x2800
	ds_read_b64_tr_b16 v[58:59], v16 offset:0x3000
	ds_read_b64_tr_b16 v[60:61], v16 offset:0x3800
	s_waitcnt lgkmcnt(0)
	s_nop 0
	v_mfma_f32_32x32x16_bf16 v[0:15], v[30:33], v[46:49], v[0:15]
	s_add_i32 s35, s35, 1
	v_lshl_add_u64 v[18:19], v[18:19], 0, s[10:11]
	v_lshl_add_u64 v[20:21], v[20:21], 0, s[10:11]
	v_lshl_add_u64 v[22:23], v[22:23], 0, s[22:23]
	s_cmp_lg_u32 s35, 34
	v_mfma_f32_32x32x16_bf16 v[0:15], v[34:37], v[50:53], v[0:15]
	v_mfma_f32_32x32x16_bf16 v[0:15], v[38:41], v[54:57], v[0:15]
	v_mfma_f32_32x32x16_bf16 v[0:15], v[42:45], v[58:61], v[0:15]
	s_cbranch_scc0 .LBB0_210

; __device__ __forceinline__ void ret_state_scan(const bf16_t* __restrict__ proj, bf16_t* __restrict__ state, int b, int h, int d4, int e2, char* lds) {
;     ...
;         if (st + 2 < 32) { FA_DMA(st + 2, (st + 2) & 3); asm volatile("s_waitcnt vmcnt(6)" ::: "memory"); }
;         else asm volatile("s_waitcnt vmcnt(0)" ::: "memory");
;         __builtin_amdgcn_s_barrier(); asm volatile("" ::: "memory");
.LBB0_250:
	s_cmp_eq_u32 s38, 1
	s_cbranch_scc1 .Lp2_w6
	s_waitcnt vmcnt(22)
	s_branch .LBB0_212
.Lp2_w6:
	s_waitcnt vmcnt(6)
	s_branch .LBB0_212
